# NA pair row-max: ds_bpermute round trips replaced by v_permlane16/32_swap
# speedup vs baseline: 1.0135x; 1.0033x over previous
; DI f32x4 mfma16(bf16x8 a, bf16x8 b, f32x4 c) { return __builtin_amdgcn_mfma_f32_16x16x32_bf16(a, b, c, 0, 0, 0); }
; DI bf16x8 pack8(f32x4 a, f32x4 b) { u32x4 v; v.x = pk2(a[0], a[1]); v.y = pk2(a[2], a[3]); v.z = pk2(b[0], b[1]); v.w = pk2(b[2], b[3]); return __builtin_bit_cast(bf16x8, v); }
; DI NaKV na_load_kv(const bf16* kbase, const bf16* vbase, int krel) {
;     NaKV f;
; #pragma unroll
;     for (int i = 0; i < 4; ++i) f.k[i] = ld16(kbase + (size_t)krel * 65536 + (i >> 1) * 16384 + (i & 1) * 32);
; #pragma unroll
;     for (int i = 0; i < 8; ++i) f.v[i] = *(const u32x2*)(vbase + (size_t)krel * 65536 + 128 * (i >> 1) + (i & 1) * 16384);
;     return f;
; DI void na_pair2(const NaKV& f, bf16x8 q0, bf16x8 q1, const float* rp  , const int (&dcv)[8], float& m, float& l, f32x4 (&o)[4]) {
;     f32x4 s0 = {0.f, 0.f, 0.f, 0.f}, s1 = {0.f, 0.f, 0.f, 0.f};
;     s0 = mfma16(f.k[0], q0, s0); s0 = mfma16(f.k[1], q1, s0);
;     s1 = mfma16(f.k[2], q0, s1); s1 = mfma16(f.k[3], q1, s1);
;     float sv[8];
; #pragma unroll
;     for (int e = 0; e < 8; ++e) sv[e] = (e < 4 ? s0[e] : s1[e - 4]) * (0.125f * 1.44269504f) + rp[dcv[e]];
;     float mx = fmaxf(fmaxf(sv[0], sv[1]), fmaxf(sv[2], sv[3])); mx = fmaxf(mx, fmaxf(fmaxf(sv[4], sv[5]), fmaxf(sv[6], sv[7])));
;     mx = fmaxf(mx, __shfl_xor(mx, 16)); mx = fmaxf(mx, __shfl_xor(mx, 32));
;     const float mn = fmaxf(m, mx), alpha = __builtin_amdgcn_exp2f(m - mn); m = mn;
;     float ps = 0.f; f32x4 p0, p1;
; #pragma unroll
;     for (int e = 0; e < 4; ++e) { p0[e] = __builtin_amdgcn_exp2f(sv[e] - mn); p1[e] = __builtin_amdgcn_exp2f(sv[4 + e] - mn); ps += p0[e] + p1[e]; }
;     l = l * alpha + ps;
;     const bf16x8 p = pack8(p0, p1);
; #pragma unroll
;     for (int db = 0; db < 4; ++db) {
;         u32x4 v; v.x = f.v[2 * db].x; v.y = f.v[2 * db].y; v.z = f.v[2 * db + 1].x; v.w = f.v[2 * db + 1].y;
;         o[db] = mfma16(__builtin_bit_cast(bf16x8, v), p, o[db] * alpha);
;     }
.LBB0_888:
	s_add_i32 s22, s57, 1
	s_min_i32 s22, s22, s51
	s_ashr_i32 s23, s22, 31
	s_lshl_b64 s[22:23], s[22:23], 17
	s_waitcnt vmcnt(16)
	v_lshl_add_u64 v[132:133], v[188:189], 0, s[22:23]
	global_load_dwordx4 v[156:159], v[132:133], off offset:1024
	global_load_dwordx4 v[148:151], v[132:133], off offset:1088
	v_add_co_u32_e32 v132, vcc, s75, v132
	s_nop 1
	v_addc_co_u32_e32 v133, vcc, 0, v133, vcc
	global_load_dwordx4 v[160:163], v[132:133], off offset:1024
	global_load_dwordx4 v[152:155], v[132:133], off offset:1088
	v_lshl_add_u64 v[132:133], v[190:191], 0, s[22:23]
	s_waitcnt vmcnt(16)
	v_add_co_u32_e32 v134, vcc, s75, v132
	s_nop 1
	v_addc_co_u32_e32 v135, vcc, 0, v133, vcc
	global_load_dwordx2 v[144:145], v[132:133], off
	global_load_dwordx2 v[140:141], v[132:133], off offset:256
	global_load_dwordx2 v[136:137], v[132:133], off offset:512
	s_nop 0
	global_load_dwordx2 v[132:133], v[132:133], off offset:768
	s_nop 0
	global_load_dwordx2 v[146:147], v[134:135], off
	global_load_dwordx2 v[142:143], v[134:135], off offset:256
	global_load_dwordx2 v[138:139], v[134:135], off offset:512
	s_nop 0
	global_load_dwordx2 v[134:135], v[134:135], off offset:768
	s_add_i32 s59, s48, s57
	s_add_i32 s56, s59, -4
	s_cmp_le_u32 s56, s52
	v_add_u32_e32 v222, s49, v205
	v_add_u32_e32 v223, s49, v206
	v_add_u32_e32 v219, s49, v207
	v_add_u32_e32 v220, s49, v208
	v_add_u32_e32 v221, s49, v209
	v_add_u32_e32 v217, s49, v210
	v_add_u32_e32 v218, s49, v211
	v_add_u32_e32 v216, s49, v212
	s_cbranch_scc0 .LBB0_890
	s_waitcnt vmcnt(14)
	v_mfma_f32_16x16x32_bf16 v[228:231], v[128:131], v[80:83], 0
	ds_read_b32 v0, v222 offset:2432
	ds_read_b32 v232, v223 offset:2432
	ds_read_b32 v233, v219 offset:2432
	ds_read_b32 v234, v220 offset:2432
	ds_read_b32 v235, v221 offset:2432
	ds_read_b32 v236, v217 offset:2432
	ds_read_b32 v237, v218 offset:2432
	v_mfma_f32_16x16x32_bf16 v[228:231], v[116:119], v[76:79], v[228:231]
	s_waitcnt vmcnt(12)
	v_mfma_f32_16x16x32_bf16 v[224:227], v[124:127], v[80:83], 0
	v_mfma_f32_16x16x32_bf16 v[224:227], v[120:123], v[76:79], v[224:227]
	s_waitcnt lgkmcnt(0)
	s_nop 3
	v_fmac_f32_e32 v237, 0x3e38aa3b, v230
	ds_read_b32 v230, v216 offset:2432
	v_fmac_f32_e32 v236, 0x3e38aa3b, v229
	v_fmac_f32_e32 v235, 0x3e38aa3b, v228
	s_waitcnt lgkmcnt(0)
	v_fmac_f32_e32 v230, 0x3e38aa3b, v231
	v_fmac_f32_e32 v234, 0x3e38aa3b, v227
	v_fmac_f32_e32 v233, 0x3e38aa3b, v226
	v_fmac_f32_e32 v232, 0x3e38aa3b, v225
	v_fmac_f32_e32 v0, 0x3e38aa3b, v224
	v_max_f32_e32 v226, v237, v230
	v_max_f32_e32 v224, v0, v232
	v_max_f32_e32 v225, v233, v234
	v_max3_f32 v226, v235, v236, v226
	v_max3_f32 v224, v224, v225, v226
	v_mov_b32_e32 v225, v224
	v_mov_b32_e32 v226, v224
	s_nop 1
	v_permlane16_swap_b32 v225, v226
	v_max_f32_e32 v224, v225, v226
	v_mov_b32_e32 v225, v224
	v_mov_b32_e32 v226, v224
	s_nop 1
	v_permlane32_swap_b32 v225, v226
	s_waitcnt lgkmcnt(0)
	v_max3_f32 v238, v214, v225, v226
	v_sub_f32_e32 v0, v0, v238
	v_exp_f32_e32 v239, v0
	v_sub_f32_e32 v0, v235, v238
	v_exp_f32_e32 v235, v0
	v_sub_f32_e32 v0, v232, v238
	v_exp_f32_e32 v224, v0
	v_sub_f32_e32 v0, v236, v238
	v_exp_f32_e32 v0, v0
	v_add_f32_e32 v225, v239, v235
	v_sub_f32_e32 v214, v214, v238
	v_exp_f32_e32 v214, v214
	v_pk_add_f32 v[226:227], v[224:225], v[0:1]
	v_sub_f32_e32 v225, v233, v238
	v_pk_add_f32 v[228:229], v[226:227], v[226:227] op_sel_hi:[0,1]
	v_sub_f32_e32 v226, v237, v238
	v_exp_f32_e32 v225, v225
	v_exp_f32_e32 v232, v226
	v_sub_f32_e32 v226, v234, v238
	v_sub_f32_e32 v228, v230, v238
	v_exp_f32_e32 v226, v226
	v_exp_f32_e32 v228, v228
	v_add_f32_e32 v227, v225, v232
	v_cvt_pk_bf16_f32 v224, v239, v224
	v_cvt_pk_bf16_f32 v225, v225, v226
	v_pk_add_f32 v[230:231], v[226:227], v[228:229]
	v_cvt_pk_bf16_f32 v226, v235, v0
	v_cvt_pk_bf16_f32 v227, v232, v228
	v_pk_mul_f32 v[98:99], v[98:99], v[214:215] op_sel_hi:[1,0]
	v_pk_mul_f32 v[96:97], v[96:97], v[214:215] op_sel_hi:[1,0]
	v_pk_mul_f32 v[94:95], v[94:95], v[214:215] op_sel_hi:[1,0]
	v_pk_mul_f32 v[92:93], v[92:93], v[214:215] op_sel_hi:[1,0]
	v_pk_mul_f32 v[90:91], v[90:91], v[214:215] op_sel_hi:[1,0]
	v_pk_mul_f32 v[88:89], v[88:89], v[214:215] op_sel_hi:[1,0]
	v_pk_mul_f32 v[86:87], v[86:87], v[214:215] op_sel_hi:[1,0]
	v_pk_mul_f32 v[84:85], v[84:85], v[214:215] op_sel_hi:[1,0]
	v_mfma_f32_16x16x32_bf16 v[96:99], v[112:115], v[224:227], v[96:99]
	v_add_f32_e32 v229, v230, v231
	v_fmac_f32_e32 v229, v213, v214
	v_mov_b32_e32 v213, v229
	v_mfma_f32_16x16x32_bf16 v[92:95], v[108:111], v[224:227], v[92:95]
	v_mov_b32_e32 v214, v238
	v_mfma_f32_16x16x32_bf16 v[88:91], v[104:107], v[224:227], v[88:91]
	v_mfma_f32_16x16x32_bf16 v[84:87], v[100:103], v[224:227], v[84:87]
; DI f32x4 mfma16(bf16x8 a, bf16x8 b, f32x4 c) { return __builtin_amdgcn_mfma_f32_16x16x32_bf16(a, b, c, 0, 0, 0); }
; DI bf16x8 pack8(f32x4 a, f32x4 b) { u32x4 v; v.x = pk2(a[0], a[1]); v.y = pk2(a[2], a[3]); v.z = pk2(b[0], b[1]); v.w = pk2(b[2], b[3]); return __builtin_bit_cast(bf16x8, v); }
; DI void na_pair2(const NaKV& f, bf16x8 q0, bf16x8 q1, const float* rp  , const int (&dcv)[8], float& m, float& l, f32x4 (&o)[4]) {
;     f32x4 s0 = {0.f, 0.f, 0.f, 0.f}, s1 = {0.f, 0.f, 0.f, 0.f};
;     s0 = mfma16(f.k[0], q0, s0); s0 = mfma16(f.k[1], q1, s0);
;     s1 = mfma16(f.k[2], q0, s1); s1 = mfma16(f.k[3], q1, s1);
;     float sv[8];
; #pragma unroll
;     for (int e = 0; e < 8; ++e) sv[e] = (e < 4 ? s0[e] : s1[e - 4]) * (0.125f * 1.44269504f) + rp[dcv[e]];
;     float mx = fmaxf(fmaxf(sv[0], sv[1]), fmaxf(sv[2], sv[3])); mx = fmaxf(mx, fmaxf(fmaxf(sv[4], sv[5]), fmaxf(sv[6], sv[7])));
;     mx = fmaxf(mx, __shfl_xor(mx, 16)); mx = fmaxf(mx, __shfl_xor(mx, 32));
;     const float mn = fmaxf(m, mx), alpha = __builtin_amdgcn_exp2f(m - mn); m = mn;
;     float ps = 0.f; f32x4 p0, p1;
; #pragma unroll
;     for (int e = 0; e < 4; ++e) { p0[e] = __builtin_amdgcn_exp2f(sv[e] - mn); p1[e] = __builtin_amdgcn_exp2f(sv[4 + e] - mn); ps += p0[e] + p1[e]; }
;     l = l * alpha + ps;
;     const bf16x8 p = pack8(p0, p1);
; #pragma unroll
;     for (int db = 0; db < 4; ++db) {
;         u32x4 v; v.x = f.v[2 * db].x; v.y = f.v[2 * db].y; v.z = f.v[2 * db + 1].x; v.w = f.v[2 * db + 1].y;
;         o[db] = mfma16(__builtin_bit_cast(bf16x8, v), p, o[db] * alpha);
;     }
.LBB0_890:
	s_cmp_lt_u32 s56, s3
	s_cselect_b64 s[22:23], -1, 0
	s_cmp_gt_u32 s56, s53
	s_cselect_b64 s[60:61], -1, 0
	s_or_b64 s[22:23], s[22:23], s[60:61]
	s_and_b64 vcc, exec, s[22:23]
	s_cbranch_vccnz .LBB0_892
	s_waitcnt vmcnt(14)
	v_mfma_f32_16x16x32_bf16 v[228:231], v[128:131], v[72:75], 0
	ds_read_b32 v0, v222 offset:2304
	ds_read_b32 v232, v223 offset:2304
	ds_read_b32 v233, v219 offset:2304
	ds_read_b32 v234, v220 offset:2304
	ds_read_b32 v235, v221 offset:2304
	ds_read_b32 v236, v217 offset:2304
	ds_read_b32 v237, v218 offset:2304
	v_mfma_f32_16x16x32_bf16 v[228:231], v[116:119], v[68:71], v[228:231]
	s_waitcnt vmcnt(12)
	v_mfma_f32_16x16x32_bf16 v[224:227], v[124:127], v[72:75], 0
	v_mfma_f32_16x16x32_bf16 v[224:227], v[120:123], v[68:71], v[224:227]
	s_waitcnt lgkmcnt(0)
	s_nop 3
	v_fmac_f32_e32 v237, 0x3e38aa3b, v230
	ds_read_b32 v230, v216 offset:2304
	v_fmac_f32_e32 v236, 0x3e38aa3b, v229
	v_fmac_f32_e32 v235, 0x3e38aa3b, v228
	s_waitcnt lgkmcnt(0)
	v_fmac_f32_e32 v230, 0x3e38aa3b, v231
	v_fmac_f32_e32 v234, 0x3e38aa3b, v227
	v_fmac_f32_e32 v233, 0x3e38aa3b, v226
	v_fmac_f32_e32 v232, 0x3e38aa3b, v225
	v_fmac_f32_e32 v0, 0x3e38aa3b, v224
	v_max_f32_e32 v226, v237, v230
	v_max_f32_e32 v224, v0, v232
	v_max_f32_e32 v225, v233, v234
	v_max3_f32 v226, v235, v236, v226
	v_max3_f32 v224, v224, v225, v226
	v_mov_b32_e32 v225, v224
	v_mov_b32_e32 v226, v224
	s_nop 1
	v_permlane16_swap_b32 v225, v226
	v_max_f32_e32 v224, v225, v226
	v_mov_b32_e32 v225, v224
	v_mov_b32_e32 v226, v224
	s_nop 1
	v_permlane32_swap_b32 v225, v226
	s_waitcnt lgkmcnt(0)
	v_max3_f32 v238, v3, v225, v226
	v_sub_f32_e32 v0, v0, v238
	v_exp_f32_e32 v239, v0
	v_sub_f32_e32 v0, v235, v238
	v_exp_f32_e32 v235, v0
	v_sub_f32_e32 v0, v232, v238
	v_exp_f32_e32 v224, v0
	v_sub_f32_e32 v0, v236, v238
	v_exp_f32_e32 v0, v0
	v_add_f32_e32 v225, v239, v235
	v_sub_f32_e32 v3, v3, v238
	v_pk_add_f32 v[226:227], v[224:225], v[0:1]
	s_nop 0
	v_pk_add_f32 v[228:229], v[226:227], v[226:227] op_sel_hi:[0,1]
	v_sub_f32_e32 v225, v233, v238
	v_sub_f32_e32 v226, v237, v238
	v_exp_f32_e32 v225, v225
	v_exp_f32_e32 v232, v226
	v_sub_f32_e32 v226, v234, v238
	v_sub_f32_e32 v228, v230, v238
	v_exp_f32_e32 v226, v226
	v_exp_f32_e32 v228, v228
	v_add_f32_e32 v227, v225, v232
	v_cvt_pk_bf16_f32 v224, v239, v224
	v_cvt_pk_bf16_f32 v225, v225, v226
	v_pk_add_f32 v[230:231], v[226:227], v[228:229]
	v_cvt_pk_bf16_f32 v226, v235, v0
	v_add_f32_e32 v229, v230, v231
	v_exp_f32_e32 v230, v3
	v_cvt_pk_bf16_f32 v227, v232, v228
	v_mov_b32_e32 v3, v238
	v_pk_mul_f32 v[50:51], v[50:51], v[230:231] op_sel_hi:[1,0]
	v_pk_mul_f32 v[48:49], v[48:49], v[230:231] op_sel_hi:[1,0]
	v_pk_mul_f32 v[46:47], v[46:47], v[230:231] op_sel_hi:[1,0]
	v_pk_mul_f32 v[44:45], v[44:45], v[230:231] op_sel_hi:[1,0]
	v_pk_mul_f32 v[42:43], v[42:43], v[230:231] op_sel_hi:[1,0]
	v_pk_mul_f32 v[40:41], v[40:41], v[230:231] op_sel_hi:[1,0]
	v_pk_mul_f32 v[38:39], v[38:39], v[230:231] op_sel_hi:[1,0]
	v_pk_mul_f32 v[36:37], v[36:37], v[230:231] op_sel_hi:[1,0]
	v_mfma_f32_16x16x32_bf16 v[48:51], v[112:115], v[224:227], v[48:51]
	v_fmac_f32_e32 v229, v204, v230
	v_mov_b32_e32 v204, v229
	v_mfma_f32_16x16x32_bf16 v[44:47], v[108:111], v[224:227], v[44:47]
	v_mfma_f32_16x16x32_bf16 v[40:43], v[104:107], v[224:227], v[40:43]
	v_mfma_f32_16x16x32_bf16 v[36:39], v[100:103], v[224:227], v[36:39]
.LBB0_892:
	s_cmp_lt_u32 s56, s12
	s_cselect_b64 s[22:23], -1, 0
	s_cmp_gt_u32 s56, s54
	s_cselect_b64 s[60:61], -1, 0
	s_or_b64 s[22:23], s[22:23], s[60:61]
	s_and_b64 vcc, exec, s[22:23]
	s_cbranch_vccnz .LBB0_894
	s_waitcnt vmcnt(14)
	v_mfma_f32_16x16x32_bf16 v[228:231], v[128:131], v[64:67], 0
	ds_read_b32 v0, v222 offset:2176
	ds_read_b32 v232, v223 offset:2176
	ds_read_b32 v233, v219 offset:2176
	ds_read_b32 v234, v220 offset:2176
	ds_read_b32 v235, v221 offset:2176
	ds_read_b32 v236, v217 offset:2176
	ds_read_b32 v237, v218 offset:2176
	v_mfma_f32_16x16x32_bf16 v[228:231], v[116:119], v[60:63], v[228:231]
	s_waitcnt vmcnt(12)
	v_mfma_f32_16x16x32_bf16 v[224:227], v[124:127], v[64:67], 0
	v_mfma_f32_16x16x32_bf16 v[224:227], v[120:123], v[60:63], v[224:227]
	s_waitcnt lgkmcnt(0)
	s_nop 3
	v_fmac_f32_e32 v237, 0x3e38aa3b, v230
	ds_read_b32 v230, v216 offset:2176
	v_fmac_f32_e32 v236, 0x3e38aa3b, v229
	v_fmac_f32_e32 v235, 0x3e38aa3b, v228
	s_waitcnt lgkmcnt(0)
	v_fmac_f32_e32 v230, 0x3e38aa3b, v231
	v_fmac_f32_e32 v234, 0x3e38aa3b, v227
	v_fmac_f32_e32 v233, 0x3e38aa3b, v226
	v_fmac_f32_e32 v232, 0x3e38aa3b, v225
	v_fmac_f32_e32 v0, 0x3e38aa3b, v224
	v_max_f32_e32 v226, v237, v230
	v_max_f32_e32 v224, v0, v232
	v_max_f32_e32 v225, v233, v234
	v_max3_f32 v226, v235, v236, v226
	v_max3_f32 v224, v224, v225, v226
	v_mov_b32_e32 v225, v224
	v_mov_b32_e32 v226, v224
	s_nop 1
	v_permlane16_swap_b32 v225, v226
	v_max_f32_e32 v224, v225, v226
	v_mov_b32_e32 v225, v224
	v_mov_b32_e32 v226, v224
	s_nop 1
	v_permlane32_swap_b32 v225, v226
	s_waitcnt lgkmcnt(0)
	v_max3_f32 v238, v215, v225, v226
	v_sub_f32_e32 v0, v0, v238
	v_exp_f32_e32 v239, v0
	v_sub_f32_e32 v0, v235, v238
	v_exp_f32_e32 v235, v0
	v_sub_f32_e32 v0, v232, v238
	v_exp_f32_e32 v224, v0
	v_sub_f32_e32 v0, v236, v238
	v_exp_f32_e32 v0, v0
	v_add_f32_e32 v225, v239, v235
	v_sub_f32_e32 v215, v215, v238
	v_pk_add_f32 v[226:227], v[224:225], v[0:1]
	s_nop 0
	v_pk_add_f32 v[228:229], v[226:227], v[226:227] op_sel_hi:[0,1]
	v_sub_f32_e32 v225, v233, v238
	v_sub_f32_e32 v226, v237, v238
	v_exp_f32_e32 v225, v225
	v_exp_f32_e32 v232, v226
	v_sub_f32_e32 v226, v234, v238
	v_sub_f32_e32 v228, v230, v238
	v_exp_f32_e32 v226, v226
	v_exp_f32_e32 v228, v228
	v_add_f32_e32 v227, v225, v232
	v_cvt_pk_bf16_f32 v224, v239, v224
	v_cvt_pk_bf16_f32 v225, v225, v226
	v_pk_add_f32 v[230:231], v[226:227], v[228:229]
	v_cvt_pk_bf16_f32 v226, v235, v0
	v_add_f32_e32 v229, v230, v231
	v_exp_f32_e32 v230, v215
	v_cvt_pk_bf16_f32 v227, v232, v228
	v_mov_b32_e32 v215, v238
	v_pk_mul_f32 v[34:35], v[34:35], v[230:231] op_sel_hi:[1,0]
	v_pk_mul_f32 v[32:33], v[32:33], v[230:231] op_sel_hi:[1,0]
	v_pk_mul_f32 v[30:31], v[30:31], v[230:231] op_sel_hi:[1,0]
	v_pk_mul_f32 v[28:29], v[28:29], v[230:231] op_sel_hi:[1,0]
	v_pk_mul_f32 v[26:27], v[26:27], v[230:231] op_sel_hi:[1,0]
	v_pk_mul_f32 v[24:25], v[24:25], v[230:231] op_sel_hi:[1,0]
	v_pk_mul_f32 v[22:23], v[22:23], v[230:231] op_sel_hi:[1,0]
	v_pk_mul_f32 v[20:21], v[20:21], v[230:231] op_sel_hi:[1,0]
	v_mfma_f32_16x16x32_bf16 v[32:35], v[112:115], v[224:227], v[32:35]
	v_fmac_f32_e32 v229, v187, v230
	v_mov_b32_e32 v187, v229
	v_mfma_f32_16x16x32_bf16 v[28:31], v[108:111], v[224:227], v[28:31]
	v_mfma_f32_16x16x32_bf16 v[24:27], v[104:107], v[224:227], v[24:27]
	v_mfma_f32_16x16x32_bf16 v[20:23], v[100:103], v[224:227], v[20:23]
; DI f32x4 mfma16(bf16x8 a, bf16x8 b, f32x4 c) { return __builtin_amdgcn_mfma_f32_16x16x32_bf16(a, b, c, 0, 0, 0); }
; DI bf16x8 pack8(f32x4 a, f32x4 b) { u32x4 v; v.x = pk2(a[0], a[1]); v.y = pk2(a[2], a[3]); v.z = pk2(b[0], b[1]); v.w = pk2(b[2], b[3]); return __builtin_bit_cast(bf16x8, v); }
; DI NaKV na_load_kv(const bf16* kbase, const bf16* vbase, int krel) {
;     NaKV f;
; #pragma unroll
;     for (int i = 0; i < 4; ++i) f.k[i] = ld16(kbase + (size_t)krel * 65536 + (i >> 1) * 16384 + (i & 1) * 32);
; #pragma unroll
;     for (int i = 0; i < 8; ++i) f.v[i] = *(const u32x2*)(vbase + (size_t)krel * 65536 + 128 * (i >> 1) + (i & 1) * 16384);
;     return f;
; DI void na_pair2(const NaKV& f, bf16x8 q0, bf16x8 q1, const float* rp  , const int (&dcv)[8], float& m, float& l, f32x4 (&o)[4]) {
;     f32x4 s0 = {0.f, 0.f, 0.f, 0.f}, s1 = {0.f, 0.f, 0.f, 0.f};
;     s0 = mfma16(f.k[0], q0, s0); s0 = mfma16(f.k[1], q1, s0);
;     s1 = mfma16(f.k[2], q0, s1); s1 = mfma16(f.k[3], q1, s1);
;     float sv[8];
; #pragma unroll
;     for (int e = 0; e < 8; ++e) sv[e] = (e < 4 ? s0[e] : s1[e - 4]) * (0.125f * 1.44269504f) + rp[dcv[e]];
;     float mx = fmaxf(fmaxf(sv[0], sv[1]), fmaxf(sv[2], sv[3])); mx = fmaxf(mx, fmaxf(fmaxf(sv[4], sv[5]), fmaxf(sv[6], sv[7])));
;     mx = fmaxf(mx, __shfl_xor(mx, 16)); mx = fmaxf(mx, __shfl_xor(mx, 32));
;     const float mn = fmaxf(m, mx), alpha = __builtin_amdgcn_exp2f(m - mn); m = mn;
;     float ps = 0.f; f32x4 p0, p1;
; #pragma unroll
;     for (int e = 0; e < 4; ++e) { p0[e] = __builtin_amdgcn_exp2f(sv[e] - mn); p1[e] = __builtin_amdgcn_exp2f(sv[4 + e] - mn); ps += p0[e] + p1[e]; }
;     l = l * alpha + ps;
;     const bf16x8 p = pack8(p0, p1);
; #pragma unroll
;     for (int db = 0; db < 4; ++db) {
;         u32x4 v; v.x = f.v[2 * db].x; v.y = f.v[2 * db].y; v.z = f.v[2 * db + 1].x; v.w = f.v[2 * db + 1].y;
;         o[db] = mfma16(__builtin_bit_cast(bf16x8, v), p, o[db] * alpha);
;     }
.LBB0_894:
	s_cmp_lt_u32 s56, s50
	s_cselect_b64 s[22:23], -1, 0
	s_cmp_gt_u32 s56, s55
	s_cselect_b64 s[60:61], -1, 0
	s_or_b64 s[22:23], s[22:23], s[60:61]
	s_and_b64 vcc, exec, s[22:23]
	s_cbranch_vccnz .LBB0_896
	s_waitcnt vmcnt(12)
	v_mfma_f32_16x16x32_bf16 v[124:127], v[124:127], v[56:59], 0
	v_mfma_f32_16x16x32_bf16 v[120:123], v[120:123], v[52:55], v[124:127]
	v_mfma_f32_16x16x32_bf16 v[124:127], v[128:131], v[56:59], 0
	v_mfma_f32_16x16x32_bf16 v[116:119], v[116:119], v[52:55], v[124:127]
	ds_read_b32 v0, v222 offset:2048
	s_nop 5
	ds_read_b32 v124, v223 offset:2048
	ds_read_b32 v125, v219 offset:2048
	ds_read_b32 v126, v220 offset:2048
	ds_read_b32 v127, v221 offset:2048
	ds_read_b32 v128, v217 offset:2048
	ds_read_b32 v129, v218 offset:2048
	s_waitcnt lgkmcnt(4)
	v_fmac_f32_e32 v125, 0x3e38aa3b, v122
	ds_read_b32 v122, v216 offset:2048
	s_waitcnt lgkmcnt(3)
	v_fmac_f32_e32 v127, 0x3e38aa3b, v116
	s_waitcnt lgkmcnt(2)
	v_fmac_f32_e32 v128, 0x3e38aa3b, v117
	s_waitcnt lgkmcnt(1)
	v_fmac_f32_e32 v129, 0x3e38aa3b, v118
	v_fmac_f32_e32 v126, 0x3e38aa3b, v123
	s_waitcnt lgkmcnt(0)
	v_fmac_f32_e32 v122, 0x3e38aa3b, v119
	v_fmac_f32_e32 v124, 0x3e38aa3b, v121
	v_fmac_f32_e32 v0, 0x3e38aa3b, v120
	v_max_f32_e32 v118, v129, v122
	v_max_f32_e32 v116, v0, v124
	v_max_f32_e32 v117, v125, v126
	v_max3_f32 v118, v127, v128, v118
	v_max3_f32 v116, v116, v117, v118
	v_mov_b32_e32 v117, v116
	v_mov_b32_e32 v118, v116
	s_nop 1
	v_permlane16_swap_b32 v117, v118
	v_max_f32_e32 v116, v117, v118
	v_mov_b32_e32 v117, v116
	v_mov_b32_e32 v118, v116
	s_nop 1
	v_permlane32_swap_b32 v117, v118
	s_waitcnt lgkmcnt(0)
	v_max3_f32 v130, v2, v117, v118
	v_sub_f32_e32 v0, v0, v130
	v_exp_f32_e32 v131, v0
	v_sub_f32_e32 v0, v127, v130
	v_exp_f32_e32 v127, v0
	v_sub_f32_e32 v0, v124, v130
	v_exp_f32_e32 v116, v0
	v_sub_f32_e32 v0, v128, v130
	v_exp_f32_e32 v0, v0
	v_add_f32_e32 v117, v131, v127
	v_sub_f32_e32 v2, v2, v130
	v_exp_f32_e32 v2, v2
	v_pk_add_f32 v[118:119], v[116:117], v[0:1]
	v_sub_f32_e32 v117, v125, v130
	v_pk_add_f32 v[120:121], v[118:119], v[118:119] op_sel_hi:[0,1]
	v_sub_f32_e32 v118, v129, v130
	v_exp_f32_e32 v117, v117
	v_exp_f32_e32 v124, v118
	v_sub_f32_e32 v118, v126, v130
	v_sub_f32_e32 v120, v122, v130
	v_exp_f32_e32 v118, v118
	v_exp_f32_e32 v120, v120
	v_add_f32_e32 v119, v117, v124
	v_cvt_pk_bf16_f32 v116, v131, v116
	v_cvt_pk_bf16_f32 v117, v117, v118
	v_pk_add_f32 v[122:123], v[118:119], v[120:121]
	v_cvt_pk_bf16_f32 v118, v127, v0
	v_cvt_pk_bf16_f32 v119, v124, v120
	v_pk_mul_f32 v[18:19], v[18:19], v[2:3] op_sel_hi:[1,0]
	v_pk_mul_f32 v[16:17], v[16:17], v[2:3] op_sel_hi:[1,0]
	v_pk_mul_f32 v[14:15], v[14:15], v[2:3] op_sel_hi:[1,0]
	v_pk_mul_f32 v[12:13], v[12:13], v[2:3] op_sel_hi:[1,0]
	v_pk_mul_f32 v[10:11], v[10:11], v[2:3] op_sel_hi:[1,0]
	v_pk_mul_f32 v[8:9], v[8:9], v[2:3] op_sel_hi:[1,0]
	v_pk_mul_f32 v[6:7], v[6:7], v[2:3] op_sel_hi:[1,0]
	v_pk_mul_f32 v[4:5], v[4:5], v[2:3] op_sel_hi:[1,0]
	v_mfma_f32_16x16x32_bf16 v[16:19], v[112:115], v[116:119], v[16:19]
	v_add_f32_e32 v121, v122, v123
	v_fmac_f32_e32 v121, v185, v2
	v_mov_b32_e32 v185, v121
	v_mfma_f32_16x16x32_bf16 v[12:15], v[108:111], v[116:119], v[12:15]
	v_mov_b32_e32 v2, v130
	v_mfma_f32_16x16x32_bf16 v[8:11], v[104:107], v[116:119], v[8:11]
	v_mfma_f32_16x16x32_bf16 v[4:7], v[100:103], v[116:119], v[4:7]
.LBB0_896:
	s_add_i32 s58, s57, 2
	s_min_i32 s22, s58, s51
	s_ashr_i32 s23, s22, 31
	s_lshl_b64 s[22:23], s[22:23], 17
	s_waitcnt vmcnt(16)
	v_lshl_add_u64 v[100:101], v[188:189], 0, s[22:23]
	global_load_dwordx4 v[124:127], v[100:101], off offset:1024
	global_load_dwordx4 v[120:123], v[100:101], off offset:1088
	v_add_co_u32_e32 v100, vcc, 0x8000, v100
	s_nop 1
	v_addc_co_u32_e32 v101, vcc, 0, v101, vcc
	global_load_dwordx4 v[128:131], v[100:101], off offset:1024
	global_load_dwordx4 v[116:119], v[100:101], off offset:1088
	v_lshl_add_u64 v[100:101], v[190:191], 0, s[22:23]
	s_waitcnt vmcnt(16)
	v_add_co_u32_e32 v102, vcc, 0x8000, v100
	s_nop 1
	v_addc_co_u32_e32 v103, vcc, 0, v101, vcc
	global_load_dwordx2 v[112:113], v[100:101], off
	global_load_dwordx2 v[108:109], v[100:101], off offset:256
	global_load_dwordx2 v[104:105], v[100:101], off offset:512
	s_nop 0
	global_load_dwordx2 v[100:101], v[100:101], off offset:768
	s_nop 0
	global_load_dwordx2 v[114:115], v[102:103], off
	global_load_dwordx2 v[110:111], v[102:103], off offset:256
	global_load_dwordx2 v[106:107], v[102:103], off offset:512
	s_nop 0
	global_load_dwordx2 v[102:103], v[102:103], off offset:768
	s_cmp_lt_i32 s57, s51
	s_cbranch_scc0 .LBB0_905
	s_add_i32 s59, s59, -3
	s_cmp_ge_u32 s59, s2
	s_cselect_b64 s[22:23], -1, 0
	s_cmp_lt_u32 s56, s52
	s_cselect_b64 s[60:61], -1, 0
	s_and_b64 s[22:23], s[22:23], s[60:61]
	s_and_b64 vcc, exec, s[22:23]
	s_cbranch_vccz .LBB0_899
; DI f32x4 mfma16(bf16x8 a, bf16x8 b, f32x4 c) { return __builtin_amdgcn_mfma_f32_16x16x32_bf16(a, b, c, 0, 0, 0); }
; DI bf16x8 pack8(f32x4 a, f32x4 b) { u32x4 v; v.x = pk2(a[0], a[1]); v.y = pk2(a[2], a[3]); v.z = pk2(b[0], b[1]); v.w = pk2(b[2], b[3]); return __builtin_bit_cast(bf16x8, v); }
; DI void na_pair2(const NaKV& f, bf16x8 q0, bf16x8 q1, const float* rp  , const int (&dcv)[8], float& m, float& l, f32x4 (&o)[4]) {
;     f32x4 s0 = {0.f, 0.f, 0.f, 0.f}, s1 = {0.f, 0.f, 0.f, 0.f};
;     s0 = mfma16(f.k[0], q0, s0); s0 = mfma16(f.k[1], q1, s0);
;     s1 = mfma16(f.k[2], q0, s1); s1 = mfma16(f.k[3], q1, s1);
;     float sv[8];
; #pragma unroll
;     for (int e = 0; e < 8; ++e) sv[e] = (e < 4 ? s0[e] : s1[e - 4]) * (0.125f * 1.44269504f) + rp[dcv[e]];
;     float mx = fmaxf(fmaxf(sv[0], sv[1]), fmaxf(sv[2], sv[3])); mx = fmaxf(mx, fmaxf(fmaxf(sv[4], sv[5]), fmaxf(sv[6], sv[7])));
;     mx = fmaxf(mx, __shfl_xor(mx, 16)); mx = fmaxf(mx, __shfl_xor(mx, 32));
;     const float mn = fmaxf(m, mx), alpha = __builtin_amdgcn_exp2f(m - mn); m = mn;
;     float ps = 0.f; f32x4 p0, p1;
; #pragma unroll
;     for (int e = 0; e < 4; ++e) { p0[e] = __builtin_amdgcn_exp2f(sv[e] - mn); p1[e] = __builtin_amdgcn_exp2f(sv[4 + e] - mn); ps += p0[e] + p1[e]; }
;     l = l * alpha + ps;
;     const bf16x8 p = pack8(p0, p1);
; #pragma unroll
;     for (int db = 0; db < 4; ++db) {
;         u32x4 v; v.x = f.v[2 * db].x; v.y = f.v[2 * db].y; v.z = f.v[2 * db + 1].x; v.w = f.v[2 * db + 1].y;
;         o[db] = mfma16(__builtin_bit_cast(bf16x8, v), p, o[db] * alpha);
;     }
; }
	s_waitcnt vmcnt(21)
	v_mfma_f32_16x16x32_bf16 v[228:231], v[160:163], v[80:83], 0
	ds_read_b32 v0, v222 offset:2560
	ds_read_b32 v232, v223 offset:2560
	ds_read_b32 v233, v219 offset:2560
	ds_read_b32 v234, v220 offset:2560
	ds_read_b32 v235, v221 offset:2560
	ds_read_b32 v236, v217 offset:2560
	ds_read_b32 v237, v218 offset:2560
	s_waitcnt vmcnt(20)
	v_mfma_f32_16x16x32_bf16 v[228:231], v[152:155], v[76:79], v[228:231]
	v_mfma_f32_16x16x32_bf16 v[224:227], v[156:159], v[80:83], 0
	v_mfma_f32_16x16x32_bf16 v[224:227], v[148:151], v[76:79], v[224:227]
	s_waitcnt lgkmcnt(0)
	s_nop 4
	v_fmac_f32_e32 v237, 0x3e38aa3b, v230
	ds_read_b32 v230, v216 offset:2560
	v_fmac_f32_e32 v236, 0x3e38aa3b, v229
	v_fmac_f32_e32 v235, 0x3e38aa3b, v228
	s_waitcnt lgkmcnt(0)
	v_fmac_f32_e32 v230, 0x3e38aa3b, v231
	v_fmac_f32_e32 v234, 0x3e38aa3b, v227
	v_fmac_f32_e32 v233, 0x3e38aa3b, v226
	v_fmac_f32_e32 v232, 0x3e38aa3b, v225
	v_fmac_f32_e32 v0, 0x3e38aa3b, v224
	v_max_f32_e32 v226, v237, v230
	v_max_f32_e32 v224, v0, v232
	v_max_f32_e32 v225, v233, v234
	v_max3_f32 v226, v235, v236, v226
	v_max3_f32 v224, v224, v225, v226
	v_mov_b32_e32 v225, v224
	v_mov_b32_e32 v226, v224
	s_nop 1
	v_permlane16_swap_b32 v225, v226
	v_max_f32_e32 v224, v225, v226
	v_mov_b32_e32 v225, v224
	v_mov_b32_e32 v226, v224
	s_nop 1
	v_permlane32_swap_b32 v225, v226
	s_waitcnt lgkmcnt(0)
	v_max3_f32 v238, v214, v225, v226
	v_sub_f32_e32 v0, v0, v238
	v_exp_f32_e32 v239, v0
	v_sub_f32_e32 v0, v235, v238
	v_exp_f32_e32 v235, v0
	v_sub_f32_e32 v0, v232, v238
	v_exp_f32_e32 v224, v0
	v_sub_f32_e32 v0, v236, v238
	v_exp_f32_e32 v0, v0
	v_add_f32_e32 v225, v239, v235
	v_sub_f32_e32 v214, v214, v238
	v_exp_f32_e32 v214, v214
	v_pk_add_f32 v[226:227], v[224:225], v[0:1]
	v_sub_f32_e32 v225, v233, v238
	v_pk_add_f32 v[228:229], v[226:227], v[226:227] op_sel_hi:[0,1]
	v_sub_f32_e32 v226, v237, v238
	v_exp_f32_e32 v225, v225
	v_exp_f32_e32 v232, v226
	v_sub_f32_e32 v226, v234, v238
	v_sub_f32_e32 v228, v230, v238
	v_exp_f32_e32 v226, v226
	v_exp_f32_e32 v228, v228
	v_add_f32_e32 v227, v225, v232
	v_cvt_pk_bf16_f32 v224, v239, v224
	v_cvt_pk_bf16_f32 v225, v225, v226
	v_pk_add_f32 v[230:231], v[226:227], v[228:229]
	v_cvt_pk_bf16_f32 v226, v235, v0
	v_cvt_pk_bf16_f32 v227, v232, v228
	v_pk_mul_f32 v[98:99], v[98:99], v[214:215] op_sel_hi:[1,0]
	v_pk_mul_f32 v[96:97], v[96:97], v[214:215] op_sel_hi:[1,0]
	v_pk_mul_f32 v[94:95], v[94:95], v[214:215] op_sel_hi:[1,0]
	v_pk_mul_f32 v[92:93], v[92:93], v[214:215] op_sel_hi:[1,0]
	v_pk_mul_f32 v[90:91], v[90:91], v[214:215] op_sel_hi:[1,0]
	v_pk_mul_f32 v[88:89], v[88:89], v[214:215] op_sel_hi:[1,0]
	v_pk_mul_f32 v[86:87], v[86:87], v[214:215] op_sel_hi:[1,0]
	v_pk_mul_f32 v[84:85], v[84:85], v[214:215] op_sel_hi:[1,0]
	s_waitcnt vmcnt(15)
	v_mfma_f32_16x16x32_bf16 v[96:99], v[144:147], v[224:227], v[96:99]
	v_add_f32_e32 v229, v230, v231
	v_fmac_f32_e32 v229, v213, v214
	v_mov_b32_e32 v213, v229
	s_waitcnt vmcnt(14)
	v_mfma_f32_16x16x32_bf16 v[92:95], v[140:143], v[224:227], v[92:95]
	v_mov_b32_e32 v214, v238
	s_waitcnt vmcnt(13)
	v_mfma_f32_16x16x32_bf16 v[88:91], v[136:139], v[224:227], v[88:91]
	s_waitcnt vmcnt(12)
	v_mfma_f32_16x16x32_bf16 v[84:87], v[132:135], v[224:227], v[84:87]
.LBB0_899:
	s_cmp_ge_u32 s59, s3
	s_cselect_b64 s[22:23], -1, 0
	s_cmp_lt_u32 s56, s53
	s_cselect_b64 s[60:61], -1, 0
	s_and_b64 s[22:23], s[22:23], s[60:61]
	s_andn2_b64 vcc, exec, s[22:23]
	s_cbranch_vccnz .LBB0_901
	s_waitcnt vmcnt(21)
	v_mfma_f32_16x16x32_bf16 v[228:231], v[160:163], v[72:75], 0
	ds_read_b32 v0, v222 offset:2432
	ds_read_b32 v232, v223 offset:2432
	ds_read_b32 v233, v219 offset:2432
	ds_read_b32 v234, v220 offset:2432
	ds_read_b32 v235, v221 offset:2432
	ds_read_b32 v236, v217 offset:2432
	ds_read_b32 v237, v218 offset:2432
	s_waitcnt vmcnt(20)
	v_mfma_f32_16x16x32_bf16 v[228:231], v[152:155], v[68:71], v[228:231]
	v_mfma_f32_16x16x32_bf16 v[224:227], v[156:159], v[72:75], 0
	v_mfma_f32_16x16x32_bf16 v[224:227], v[148:151], v[68:71], v[224:227]
	s_waitcnt lgkmcnt(0)
	s_nop 4
	v_fmac_f32_e32 v237, 0x3e38aa3b, v230
	ds_read_b32 v230, v216 offset:2432
	v_fmac_f32_e32 v236, 0x3e38aa3b, v229
	v_fmac_f32_e32 v235, 0x3e38aa3b, v228
	s_waitcnt lgkmcnt(0)
	v_fmac_f32_e32 v230, 0x3e38aa3b, v231
	v_fmac_f32_e32 v234, 0x3e38aa3b, v227
	v_fmac_f32_e32 v233, 0x3e38aa3b, v226
	v_fmac_f32_e32 v232, 0x3e38aa3b, v225
	v_fmac_f32_e32 v0, 0x3e38aa3b, v224
	v_max_f32_e32 v226, v237, v230
	v_max_f32_e32 v224, v0, v232
	v_max_f32_e32 v225, v233, v234
	v_max3_f32 v226, v235, v236, v226
	v_max3_f32 v224, v224, v225, v226
	v_mov_b32_e32 v225, v224
	v_mov_b32_e32 v226, v224
	s_nop 1
	v_permlane16_swap_b32 v225, v226
	v_max_f32_e32 v224, v225, v226
	v_mov_b32_e32 v225, v224
	v_mov_b32_e32 v226, v224
	s_nop 1
	v_permlane32_swap_b32 v225, v226
	s_waitcnt lgkmcnt(0)
	v_max3_f32 v238, v3, v225, v226
	v_sub_f32_e32 v0, v0, v238
	v_exp_f32_e32 v239, v0
	v_sub_f32_e32 v0, v235, v238
	v_exp_f32_e32 v235, v0
	v_sub_f32_e32 v0, v232, v238
	v_exp_f32_e32 v224, v0
	v_sub_f32_e32 v0, v236, v238
	v_exp_f32_e32 v0, v0
	v_add_f32_e32 v225, v239, v235
	v_sub_f32_e32 v3, v3, v238
	v_pk_add_f32 v[226:227], v[224:225], v[0:1]
	s_nop 0
	v_pk_add_f32 v[228:229], v[226:227], v[226:227] op_sel_hi:[0,1]
	v_sub_f32_e32 v225, v233, v238
	v_sub_f32_e32 v226, v237, v238
	v_exp_f32_e32 v225, v225
	v_exp_f32_e32 v232, v226
	v_sub_f32_e32 v226, v234, v238
	v_sub_f32_e32 v228, v230, v238
	v_exp_f32_e32 v226, v226
	v_exp_f32_e32 v228, v228
	v_add_f32_e32 v227, v225, v232
	v_cvt_pk_bf16_f32 v224, v239, v224
	v_cvt_pk_bf16_f32 v225, v225, v226
	v_pk_add_f32 v[230:231], v[226:227], v[228:229]
	v_cvt_pk_bf16_f32 v226, v235, v0
	v_add_f32_e32 v229, v230, v231
	v_exp_f32_e32 v230, v3
	v_cvt_pk_bf16_f32 v227, v232, v228
	v_mov_b32_e32 v3, v238
	v_pk_mul_f32 v[50:51], v[50:51], v[230:231] op_sel_hi:[1,0]
	v_pk_mul_f32 v[48:49], v[48:49], v[230:231] op_sel_hi:[1,0]
	v_pk_mul_f32 v[46:47], v[46:47], v[230:231] op_sel_hi:[1,0]
	v_pk_mul_f32 v[44:45], v[44:45], v[230:231] op_sel_hi:[1,0]
	v_pk_mul_f32 v[42:43], v[42:43], v[230:231] op_sel_hi:[1,0]
	v_pk_mul_f32 v[40:41], v[40:41], v[230:231] op_sel_hi:[1,0]
	v_pk_mul_f32 v[38:39], v[38:39], v[230:231] op_sel_hi:[1,0]
	v_pk_mul_f32 v[36:37], v[36:37], v[230:231] op_sel_hi:[1,0]
	s_waitcnt vmcnt(15)
	v_mfma_f32_16x16x32_bf16 v[48:51], v[144:147], v[224:227], v[48:51]
	v_fmac_f32_e32 v229, v204, v230
	v_mov_b32_e32 v204, v229
	s_waitcnt vmcnt(14)
	v_mfma_f32_16x16x32_bf16 v[44:47], v[140:143], v[224:227], v[44:47]
	s_waitcnt vmcnt(13)
	v_mfma_f32_16x16x32_bf16 v[40:43], v[136:139], v[224:227], v[40:43]
	s_waitcnt vmcnt(12)
	v_mfma_f32_16x16x32_bf16 v[36:39], v[132:135], v[224:227], v[36:39]
; DI f32x4 mfma16(bf16x8 a, bf16x8 b, f32x4 c) { return __builtin_amdgcn_mfma_f32_16x16x32_bf16(a, b, c, 0, 0, 0); }
; DI bf16x8 pack8(f32x4 a, f32x4 b) { u32x4 v; v.x = pk2(a[0], a[1]); v.y = pk2(a[2], a[3]); v.z = pk2(b[0], b[1]); v.w = pk2(b[2], b[3]); return __builtin_bit_cast(bf16x8, v); }
; DI void na_pair2(const NaKV& f, bf16x8 q0, bf16x8 q1, const float* rp  , const int (&dcv)[8], float& m, float& l, f32x4 (&o)[4]) {
;     f32x4 s0 = {0.f, 0.f, 0.f, 0.f}, s1 = {0.f, 0.f, 0.f, 0.f};
;     s0 = mfma16(f.k[0], q0, s0); s0 = mfma16(f.k[1], q1, s0);
;     s1 = mfma16(f.k[2], q0, s1); s1 = mfma16(f.k[3], q1, s1);
;     float sv[8];
; #pragma unroll
;     for (int e = 0; e < 8; ++e) sv[e] = (e < 4 ? s0[e] : s1[e - 4]) * (0.125f * 1.44269504f) + rp[dcv[e]];
;     float mx = fmaxf(fmaxf(sv[0], sv[1]), fmaxf(sv[2], sv[3])); mx = fmaxf(mx, fmaxf(fmaxf(sv[4], sv[5]), fmaxf(sv[6], sv[7])));
;     mx = fmaxf(mx, __shfl_xor(mx, 16)); mx = fmaxf(mx, __shfl_xor(mx, 32));
;     const float mn = fmaxf(m, mx), alpha = __builtin_amdgcn_exp2f(m - mn); m = mn;
;     float ps = 0.f; f32x4 p0, p1;
; #pragma unroll
;     for (int e = 0; e < 4; ++e) { p0[e] = __builtin_amdgcn_exp2f(sv[e] - mn); p1[e] = __builtin_amdgcn_exp2f(sv[4 + e] - mn); ps += p0[e] + p1[e]; }
;     l = l * alpha + ps;
;     const bf16x8 p = pack8(p0, p1);
; #pragma unroll
;     for (int db = 0; db < 4; ++db) {
;         u32x4 v; v.x = f.v[2 * db].x; v.y = f.v[2 * db].y; v.z = f.v[2 * db + 1].x; v.w = f.v[2 * db + 1].y;
;         o[db] = mfma16(__builtin_bit_cast(bf16x8, v), p, o[db] * alpha);
;     }
; }
.LBB0_901:
	s_cmp_ge_u32 s59, s12
	s_cselect_b64 s[22:23], -1, 0
	s_cmp_lt_u32 s56, s54
	s_cselect_b64 s[60:61], -1, 0
	s_and_b64 s[22:23], s[22:23], s[60:61]
	s_andn2_b64 vcc, exec, s[22:23]
	s_cbranch_vccnz .LBB0_903
	s_waitcnt vmcnt(21)
	v_mfma_f32_16x16x32_bf16 v[228:231], v[160:163], v[64:67], 0
	ds_read_b32 v0, v222 offset:2304
	ds_read_b32 v232, v223 offset:2304
	ds_read_b32 v233, v219 offset:2304
	ds_read_b32 v234, v220 offset:2304
	ds_read_b32 v235, v221 offset:2304
	ds_read_b32 v236, v217 offset:2304
	ds_read_b32 v237, v218 offset:2304
	s_waitcnt vmcnt(20)
	v_mfma_f32_16x16x32_bf16 v[228:231], v[152:155], v[60:63], v[228:231]
	v_mfma_f32_16x16x32_bf16 v[224:227], v[156:159], v[64:67], 0
	v_mfma_f32_16x16x32_bf16 v[224:227], v[148:151], v[60:63], v[224:227]
	s_waitcnt lgkmcnt(0)
	s_nop 4
	v_fmac_f32_e32 v237, 0x3e38aa3b, v230
	ds_read_b32 v230, v216 offset:2304
	v_fmac_f32_e32 v236, 0x3e38aa3b, v229
	v_fmac_f32_e32 v235, 0x3e38aa3b, v228
	s_waitcnt lgkmcnt(0)
	v_fmac_f32_e32 v230, 0x3e38aa3b, v231
	v_fmac_f32_e32 v234, 0x3e38aa3b, v227
	v_fmac_f32_e32 v233, 0x3e38aa3b, v226
	v_fmac_f32_e32 v232, 0x3e38aa3b, v225
	v_fmac_f32_e32 v0, 0x3e38aa3b, v224
	v_max_f32_e32 v226, v237, v230
	v_max_f32_e32 v224, v0, v232
	v_max_f32_e32 v225, v233, v234
	v_max3_f32 v226, v235, v236, v226
	v_max3_f32 v224, v224, v225, v226
	v_mov_b32_e32 v225, v224
	v_mov_b32_e32 v226, v224
	s_nop 1
	v_permlane16_swap_b32 v225, v226
	v_max_f32_e32 v224, v225, v226
	v_mov_b32_e32 v225, v224
	v_mov_b32_e32 v226, v224
	s_nop 1
	v_permlane32_swap_b32 v225, v226
	s_waitcnt lgkmcnt(0)
	v_max3_f32 v238, v215, v225, v226
	v_sub_f32_e32 v0, v0, v238
	v_exp_f32_e32 v239, v0
	v_sub_f32_e32 v0, v235, v238
	v_exp_f32_e32 v235, v0
	v_sub_f32_e32 v0, v232, v238
	v_exp_f32_e32 v224, v0
	v_sub_f32_e32 v0, v236, v238
	v_exp_f32_e32 v0, v0
	v_add_f32_e32 v225, v239, v235
	v_sub_f32_e32 v215, v215, v238
	v_pk_add_f32 v[226:227], v[224:225], v[0:1]
	s_nop 0
	v_pk_add_f32 v[228:229], v[226:227], v[226:227] op_sel_hi:[0,1]
	v_sub_f32_e32 v225, v233, v238
	v_sub_f32_e32 v226, v237, v238
	v_exp_f32_e32 v225, v225
	v_exp_f32_e32 v232, v226
	v_sub_f32_e32 v226, v234, v238
	v_sub_f32_e32 v228, v230, v238
	v_exp_f32_e32 v226, v226
	v_exp_f32_e32 v228, v228
	v_add_f32_e32 v227, v225, v232
	v_cvt_pk_bf16_f32 v224, v239, v224
	v_cvt_pk_bf16_f32 v225, v225, v226
	v_pk_add_f32 v[230:231], v[226:227], v[228:229]
	v_cvt_pk_bf16_f32 v226, v235, v0
	v_add_f32_e32 v229, v230, v231
	v_exp_f32_e32 v230, v215
	v_cvt_pk_bf16_f32 v227, v232, v228
	v_mov_b32_e32 v215, v238
	v_pk_mul_f32 v[34:35], v[34:35], v[230:231] op_sel_hi:[1,0]
	v_pk_mul_f32 v[32:33], v[32:33], v[230:231] op_sel_hi:[1,0]
	v_pk_mul_f32 v[30:31], v[30:31], v[230:231] op_sel_hi:[1,0]
	v_pk_mul_f32 v[28:29], v[28:29], v[230:231] op_sel_hi:[1,0]
	v_pk_mul_f32 v[26:27], v[26:27], v[230:231] op_sel_hi:[1,0]
	v_pk_mul_f32 v[24:25], v[24:25], v[230:231] op_sel_hi:[1,0]
	v_pk_mul_f32 v[22:23], v[22:23], v[230:231] op_sel_hi:[1,0]
	v_pk_mul_f32 v[20:21], v[20:21], v[230:231] op_sel_hi:[1,0]
	s_waitcnt vmcnt(15)
	v_mfma_f32_16x16x32_bf16 v[32:35], v[144:147], v[224:227], v[32:35]
	v_fmac_f32_e32 v229, v187, v230
	v_mov_b32_e32 v187, v229
	s_waitcnt vmcnt(14)
	v_mfma_f32_16x16x32_bf16 v[28:31], v[140:143], v[224:227], v[28:31]
	s_waitcnt vmcnt(13)
	v_mfma_f32_16x16x32_bf16 v[24:27], v[136:139], v[224:227], v[24:27]
	s_waitcnt vmcnt(12)
	v_mfma_f32_16x16x32_bf16 v[20:23], v[132:135], v[224:227], v[20:23]
.LBB0_903:
	s_cmp_ge_u32 s59, s50
	s_cselect_b64 s[22:23], -1, 0
	s_cmp_lt_u32 s56, s55
	s_cselect_b64 s[56:57], -1, 0
	s_and_b64 s[22:23], s[22:23], s[56:57]
	s_andn2_b64 vcc, exec, s[22:23]
	s_cbranch_vccnz .LBB0_905
	s_waitcnt vmcnt(21)
	v_mfma_f32_16x16x32_bf16 v[160:163], v[160:163], v[56:59], 0
	ds_read_b32 v0, v222 offset:2176
	ds_read_b32 v222, v223 offset:2176
	ds_read_b32 v219, v219 offset:2176
	ds_read_b32 v220, v220 offset:2176
	ds_read_b32 v221, v221 offset:2176
	ds_read_b32 v217, v217 offset:2176
	ds_read_b32 v218, v218 offset:2176
	ds_read_b32 v216, v216 offset:2176
	v_mfma_f32_16x16x32_bf16 v[156:159], v[156:159], v[56:59], 0
	s_waitcnt vmcnt(20)
	v_mfma_f32_16x16x32_bf16 v[152:155], v[152:155], v[52:55], v[160:163]
	v_mfma_f32_16x16x32_bf16 v[148:151], v[148:151], v[52:55], v[156:159]
	s_waitcnt lgkmcnt(1)
	s_nop 5
	v_fmac_f32_e32 v218, 0x3e38aa3b, v154
	s_waitcnt lgkmcnt(0)
	v_fmac_f32_e32 v216, 0x3e38aa3b, v155
	v_fmac_f32_e32 v217, 0x3e38aa3b, v153
	v_fmac_f32_e32 v221, 0x3e38aa3b, v152
	v_fmac_f32_e32 v220, 0x3e38aa3b, v151
	v_fmac_f32_e32 v219, 0x3e38aa3b, v150
	v_fmac_f32_e32 v222, 0x3e38aa3b, v149
	v_fmac_f32_e32 v0, 0x3e38aa3b, v148
	v_max_f32_e32 v150, v218, v216
	v_max_f32_e32 v148, v0, v222
	v_max_f32_e32 v149, v219, v220
	v_max3_f32 v150, v221, v217, v150
	v_max3_f32 v148, v148, v149, v150
	v_mov_b32_e32 v149, v148
	v_mov_b32_e32 v150, v148
	s_nop 1
	v_permlane16_swap_b32 v149, v150
	v_max_f32_e32 v148, v149, v150
	v_mov_b32_e32 v149, v148
	v_mov_b32_e32 v150, v148
	s_nop 1
	v_permlane32_swap_b32 v149, v150
	s_waitcnt lgkmcnt(0)
	v_max3_f32 v156, v2, v149, v150
	v_sub_f32_e32 v0, v0, v156
	v_exp_f32_e32 v157, v0
	v_sub_f32_e32 v0, v221, v156
	v_exp_f32_e32 v158, v0
	v_sub_f32_e32 v0, v222, v156
	v_exp_f32_e32 v148, v0
	v_sub_f32_e32 v0, v217, v156
	v_exp_f32_e32 v0, v0
	v_sub_f32_e32 v149, v219, v156
	v_exp_f32_e32 v159, v149
	v_sub_f32_e32 v149, v218, v156
	v_exp_f32_e32 v160, v149
	v_add_f32_e32 v149, v157, v158
	v_pk_add_f32 v[150:151], v[148:149], v[0:1]
	v_sub_f32_e32 v149, v220, v156
	v_sub_f32_e32 v2, v2, v156
	v_pk_add_f32 v[152:153], v[150:151], v[150:151] op_sel_hi:[0,1]
	v_exp_f32_e32 v154, v149
	v_sub_f32_e32 v149, v216, v156
	v_exp_f32_e32 v152, v149
	v_exp_f32_e32 v2, v2
	v_add_f32_e32 v155, v159, v160
	v_cvt_pk_bf16_f32 v148, v157, v148
	v_cvt_pk_bf16_f32 v149, v159, v154
	v_cvt_pk_bf16_f32 v150, v158, v0
	v_cvt_pk_bf16_f32 v151, v160, v152
	v_pk_mul_f32 v[18:19], v[18:19], v[2:3] op_sel_hi:[1,0]
	v_pk_mul_f32 v[16:17], v[16:17], v[2:3] op_sel_hi:[1,0]
	v_pk_mul_f32 v[14:15], v[14:15], v[2:3] op_sel_hi:[1,0]
	v_pk_mul_f32 v[12:13], v[12:13], v[2:3] op_sel_hi:[1,0]
	v_pk_mul_f32 v[10:11], v[10:11], v[2:3] op_sel_hi:[1,0]
	v_pk_mul_f32 v[8:9], v[8:9], v[2:3] op_sel_hi:[1,0]
	v_pk_mul_f32 v[6:7], v[6:7], v[2:3] op_sel_hi:[1,0]
	v_pk_mul_f32 v[4:5], v[4:5], v[2:3] op_sel_hi:[1,0]
	s_waitcnt vmcnt(15)
	v_mfma_f32_16x16x32_bf16 v[16:19], v[144:147], v[148:151], v[16:19]
	v_add_f32_e64 v144, v154, v152
	v_add_f32_e64 v145, v155, v153
	v_add_f32_e32 v0, v144, v145
	s_waitcnt vmcnt(14)
	v_mfma_f32_16x16x32_bf16 v[12:15], v[140:143], v[148:151], v[12:15]
	v_fmac_f32_e32 v0, v185, v2
	v_mov_b32_e32 v2, v156
	v_mov_b32_e32 v185, v0
	s_waitcnt vmcnt(13)
	v_mfma_f32_16x16x32_bf16 v[8:11], v[136:139], v[148:151], v[8:11]
	s_waitcnt vmcnt(12)
	v_mfma_f32_16x16x32_bf16 v[4:7], v[132:135], v[148:151], v[4:7]
